# att_final: eight subln_g gain loads issued up front; per-step vmcnt(0) drains removed
# baseline (speedup 1.0000x reference)
; __device__ __forceinline__ float wave_sum(float v) { return wave_sum_fast(v); }
;     __device__ __forceinline__ const float* in(int i) const { return (const float*)ptr(i); }
; __device__ __forceinline__ void att_final(const AttAcc& A, float l0, float l1, float lam, const float* subg, bf16_t* orow, int g) {
;     const float i0 = 1.f / l0, i1 = lam / l1;
;     f32x4 o[8]; float ss = 0.f;
; #pragma unroll
;     for (int d = 0; d < 8; ++d) { o[d] = A.O[0][d] * i0 - A.O[1][d] * i1; ss += (o[d][0] * o[d][0] + o[d][1] * o[d][1]) + (o[d][2] * o[d][2] + o[d][3] * o[d][3]); }
; __device__ __forceinline__ float att_lambda(const Ctx& p, int lane) {
;     const float a = wave_sum(p.in(12)[lane] * p.in(13)[lane]), b = wave_sum(p.in(14)[lane] * p.in(15)[lane]);
;     return expf(a) - expf(b) + 0.2f;
; }
; __device__ __forceinline__ void att_prompt_unit(const Ctx& p, int bh, int qb, LAS unsigned char* lds) {
;     ...
;     float l0 = A.l[0], l1 = A.l[1];
;     l0 += __shfl_xor(l0, 16); l0 += __shfl_xor(l0, 32); l1 += __shfl_xor(l1, 16); l1 += __shfl_xor(l1, 32);
;     const float lam = att_lambda(p, lane);
;     att_final(A, l0, l1, lam, p.in(16), qrow, g);
.LBB0_1782:
	v_mov_b32_e32 v0, s24
	s_barrier
	ds_read_b128 v[68:71], v0
	v_mov_b32_e32 v2, s25
	ds_read_b128 v[72:75], v2
	v_lshlrev_b32_e32 v0, 2, v132
	v_mov_b32_e32 v2, s34
	s_waitcnt lgkmcnt(1)
	v_readfirstlane_b32 s2, v68
	v_readfirstlane_b32 s3, v69
	v_readfirstlane_b32 s14, v70
	v_readfirstlane_b32 s15, v71
	ds_read_b64 v[2:3], v2
	s_waitcnt lgkmcnt(1)
	v_readfirstlane_b32 s16, v72
	v_readfirstlane_b32 s17, v73
	v_readfirstlane_b32 s44, v74
	v_readfirstlane_b32 s45, v75
	global_load_dword v68, v0, s[2:3]
	global_load_dword v69, v0, s[14:15]
	s_nop 0
	global_load_dword v70, v0, s[16:17]
	s_nop 0
	global_load_dword v71, v0, s[44:45]
	v_and_b32_e32 v72, 64, v143
	v_xor_b32_e32 v0, 16, v143
	v_add_u32_e32 v72, 64, v72
	v_cmp_lt_i32_e32 vcc, v0, v72
	v_xor_b32_e32 v73, 32, v143
	s_waitcnt lgkmcnt(0)
	v_readfirstlane_b32 s14, v2
	v_cndmask_b32_e32 v0, v143, v0, vcc
	v_lshlrev_b32_e32 v74, 2, v0
	ds_bpermute_b32 v0, v74, v137
	v_cmp_lt_i32_e32 vcc, v73, v72
	v_readfirstlane_b32 s15, v3
	s_waitcnt lgkmcnt(0)
	v_add_f32_e32 v0, v137, v0
	v_cndmask_b32_e32 v72, v143, v73, vcc
	v_lshlrev_b32_e32 v72, 2, v72
	ds_bpermute_b32 v75, v72, v0
	ds_bpermute_b32 v73, v74, v139
	s_waitcnt lgkmcnt(1)
	v_add_f32_e32 v0, v0, v75
	v_div_scale_f32 v2, s[2:3], v0, v0, 1.0
	s_waitcnt lgkmcnt(0)
	v_add_f32_e32 v3, v139, v73
	v_rcp_f32_e32 v73, v2
	v_div_scale_f32 v75, vcc, 1.0, v0, 1.0
	ds_bpermute_b32 v149, v72, v3
	v_fma_f32 v76, -v2, v73, 1.0
	v_fmac_f32_e32 v73, v76, v73
	v_mul_f32_e32 v76, v75, v73
	v_fma_f32 v77, -v2, v76, v75
	v_fmac_f32_e32 v76, v77, v73
	v_fma_f32 v2, -v2, v76, v75
	v_div_fmas_f32 v73, v2, v73, v76
	v_div_fixup_f32 v0, v73, v0, 1.0
	s_waitcnt vmcnt(2)
	v_mul_f32_e32 v75, v68, v69
	s_nop 1
	v_mov_b32_dpp v75, v75 quad_perm:[1,0,3,2] row_mask:0xf bank_mask:0xf bound_ctrl:1
	s_waitcnt vmcnt(0)
	v_mul_f32_e32 v77, v70, v71
	v_fmac_f32_e32 v75, v68, v69
	s_nop 0
	v_mov_b32_dpp v77, v77 quad_perm:[1,0,3,2] row_mask:0xf bank_mask:0xf bound_ctrl:1
	v_fmac_f32_e32 v77, v70, v71
	v_add_f32_dpp v68, v75, v75 quad_perm:[2,3,0,1] row_mask:0xf bank_mask:0xf bound_ctrl:1
	s_nop 0
	v_add_f32_dpp v69, v77, v77 quad_perm:[2,3,0,1] row_mask:0xf bank_mask:0xf bound_ctrl:1
	v_add_f32_dpp v68, v68, v68 row_half_mirror row_mask:0xf bank_mask:0xf bound_ctrl:1
	s_nop 0
	v_add_f32_dpp v69, v69, v69 row_half_mirror row_mask:0xf bank_mask:0xf bound_ctrl:1
	v_add_f32_dpp v68, v68, v68 row_mirror row_mask:0xf bank_mask:0xf bound_ctrl:1
	v_mov_b32_e32 v70, v68
	v_add_f32_dpp v69, v69, v69 row_mirror row_mask:0xf bank_mask:0xf bound_ctrl:1
	v_mov_b32_e32 v71, v69
	v_permlane16_swap_b32_e32 v68, v70
	s_nop 0
	v_permlane16_swap_b32_e32 v69, v71
	v_add_f32_e32 v68, v68, v70
	v_add_f32_e32 v69, v69, v71
	v_mov_b32_e32 v70, v68
	v_mov_b32_e32 v71, v69
	s_nop 0
	v_permlane32_swap_b32_e32 v68, v70
	v_permlane32_swap_b32_e32 v69, v71
	v_add_f32_e32 v68, v68, v70
	v_add_f32_e32 v69, v69, v71
	v_mul_f32_e32 v70, 0x3fb8aa3b, v68
	v_mul_f32_e32 v71, 0x3fb8aa3b, v69
	v_fma_f32 v75, v68, s26, -v70
	v_rndne_f32_e32 v77, v70
	v_fma_f32 v78, v69, s26, -v71
	v_rndne_f32_e32 v79, v71
	v_fmac_f32_e32 v75, 0x32a5705f, v68
	v_sub_f32_e32 v70, v70, v77
	v_fmac_f32_e32 v78, 0x32a5705f, v69
	v_sub_f32_e32 v71, v71, v79
	v_add_f32_e32 v70, v70, v75
	v_cvt_i32_f32_e32 v77, v77
	v_add_f32_e32 v71, v71, v78
	v_exp_f32_e32 v70, v70
	v_cvt_i32_f32_e32 v79, v79
	v_exp_f32_e32 v71, v71
	v_cmp_ngt_f32_e32 vcc, s27, v68
	v_ldexp_f32 v2, v70, v77
	v_ldexp_f32 v70, v71, v79
	v_cndmask_b32_e32 v2, 0, v2, vcc
	v_cmp_ngt_f32_e32 vcc, s27, v69
	s_nop 1
	v_cndmask_b32_e32 v70, 0, v70, vcc
	v_cmp_nlt_f32_e32 vcc, s33, v68
	s_nop 1
	v_cndmask_b32_e32 v2, v168, v2, vcc
	v_cmp_nlt_f32_e32 vcc, s33, v69
	s_nop 1
	v_cndmask_b32_e32 v68, v168, v70, vcc
	v_sub_f32_e32 v2, v2, v68
	s_waitcnt lgkmcnt(0)
	v_pk_add_f32 v[2:3], v[2:3], v[148:149]
	s_nop 0
	v_div_scale_f32 v68, s[2:3], v3, v3, v2
	v_rcp_f32_e32 v69, v68
	v_div_scale_f32 v70, vcc, v2, v3, v2
	v_fma_f32 v71, -v68, v69, 1.0
	v_fmac_f32_e32 v69, v71, v69
	v_mul_f32_e32 v71, v70, v69
	v_fma_f32 v73, -v68, v71, v70
	v_fmac_f32_e32 v71, v73, v69
	v_fma_f32 v68, -v68, v71, v70
	v_div_fmas_f32 v68, v68, v69, v71
	v_div_fixup_f32 v2, v68, v3, v2
	v_pk_mul_f32 v[60:61], v[60:61], v[2:3] op_sel_hi:[1,0]
	v_pk_mul_f32 v[52:53], v[52:53], v[2:3] op_sel_hi:[1,0]
	v_pk_mul_f32 v[62:63], v[62:63], v[2:3] op_sel_hi:[1,0]
	v_pk_fma_f32 v[60:61], v[64:65], v[0:1], v[60:61] op_sel_hi:[1,0,1] neg_lo:[0,0,1] neg_hi:[0,0,1]
	v_pk_mul_f32 v[54:55], v[54:55], v[2:3] op_sel_hi:[1,0]
	v_pk_fma_f32 v[52:53], v[56:57], v[0:1], v[52:53] op_sel_hi:[1,0,1] neg_lo:[0,0,1] neg_hi:[0,0,1]
	v_pk_fma_f32 v[62:63], v[66:67], v[0:1], v[62:63] op_sel_hi:[1,0,1] neg_lo:[0,0,1] neg_hi:[0,0,1]
	v_pk_fma_f32 v[54:55], v[58:59], v[0:1], v[54:55] op_sel_hi:[1,0,1] neg_lo:[0,0,1] neg_hi:[0,0,1]
	v_mov_b32_e32 v58, v61
	v_mov_b32_e32 v59, v53
	v_mov_b32_e32 v56, v60
	v_mov_b32_e32 v57, v52
	v_pk_mul_f32 v[58:59], v[58:59], v[58:59]
	v_mov_b32_e32 v64, v63
	v_mov_b32_e32 v65, v55
	v_pk_mul_f32 v[46:47], v[46:47], v[2:3] op_sel_hi:[1,0]
	v_pk_mul_f32 v[44:45], v[44:45], v[2:3] op_sel_hi:[1,0]
	v_pk_mul_f32 v[36:37], v[36:37], v[2:3] op_sel_hi:[1,0]
	v_pk_fma_f32 v[56:57], v[56:57], v[56:57], v[58:59]
	v_mov_b32_e32 v58, v62
	v_mov_b32_e32 v59, v54
	v_pk_mul_f32 v[64:65], v[64:65], v[64:65]
	v_pk_fma_f32 v[44:45], v[48:49], v[0:1], v[44:45] op_sel_hi:[1,0,1] neg_lo:[0,0,1] neg_hi:[0,0,1]
	v_pk_fma_f32 v[46:47], v[50:51], v[0:1], v[46:47] op_sel_hi:[1,0,1] neg_lo:[0,0,1] neg_hi:[0,0,1]
	v_pk_fma_f32 v[36:37], v[40:41], v[0:1], v[36:37] op_sel_hi:[1,0,1] neg_lo:[0,0,1] neg_hi:[0,0,1]
; __device__ __forceinline__ void att_final(const AttAcc& A, float l0, float l1, float lam, const float* subg, bf16_t* orow, int g) {
;     ...
;     for (int d = 0; d < 8; ++d) { o[d] = A.O[0][d] * i0 - A.O[1][d] * i1; ss += (o[d][0] * o[d][0] + o[d][1] * o[d][1]) + (o[d][2] * o[d][2] + o[d][3] * o[d][3]); }
;     ss += __shfl_xor(ss, 16); ss += __shfl_xor(ss, 32);
;     const float rs = 0.8f / sqrtf(ss * (1.f / 128.f) + EPS);
; #pragma unroll
;     for (int d = 0; d < 8; ++d) { const f32x4 gg = *(const f32x4*)(subg + 16 * d + 4 * g);
	v_pk_fma_f32 v[58:59], v[58:59], v[58:59], v[64:65]
	v_pk_mul_f32 v[48:49], v[46:47], v[46:47]
	v_pk_mul_f32 v[50:51], v[44:45], v[44:45]
	v_pk_mul_f32 v[38:39], v[38:39], v[2:3] op_sel_hi:[1,0]
	v_mul_f32_e32 v40, v36, v36
	v_pk_add_f32 v[56:57], v[56:57], v[58:59]
	v_pk_mov_b32 v[58:59], v[50:51], v[48:49] op_sel:[1,0]
	v_mov_b32_e32 v51, v49
	v_pk_fma_f32 v[38:39], v[42:43], v[0:1], v[38:39] op_sel_hi:[1,0,1] neg_lo:[0,0,1] neg_hi:[0,0,1]
	v_pk_fma_f32 v[40:41], v[36:37], v[36:37], v[40:41] op_sel_hi:[1,1,0]
	v_pk_add_f32 v[48:49], v[58:59], v[50:51]
	v_mul_f32_e32 v40, v38, v38
	v_pk_mul_f32 v[32:33], v[32:33], v[2:3] op_sel_hi:[1,0]
	v_pk_mul_f32 v[34:35], v[34:35], v[2:3] op_sel_hi:[1,0]
	v_pk_add_f32 v[56:57], v[56:57], v[56:57] op_sel_hi:[0,1]
	v_pk_add_f32 v[48:49], v[48:49], v[48:49] op_sel_hi:[0,1]
	v_pk_fma_f32 v[42:43], v[38:39], v[38:39], v[40:41] op_sel_hi:[1,1,0]
	v_pk_fma_f32 v[30:31], v[30:31], v[0:1], v[34:35] op_sel_hi:[1,0,1] neg_lo:[0,0,1] neg_hi:[0,0,1]
	v_pk_fma_f32 v[28:29], v[28:29], v[0:1], v[32:33] op_sel_hi:[1,0,1] neg_lo:[0,0,1] neg_hi:[0,0,1]
	v_mul_f32_e32 v48, v30, v30
	v_mul_f32_e32 v40, v28, v28
	v_mul_f32_e32 v42, v29, v29
	v_mul_f32_e32 v56, v31, v31
	v_pk_add_f32 v[32:33], v[40:41], v[42:43]
	v_pk_add_f32 v[34:35], v[48:49], v[56:57]
	v_pk_mul_f32 v[24:25], v[24:25], v[2:3] op_sel_hi:[1,0]
	v_lshlrev_b32_e32 v48, 2, v134
	v_pk_add_f32 v[32:33], v[32:33], v[34:35]
	v_pk_mul_f32 v[34:35], v[26:27], v[2:3] op_sel_hi:[1,0]
	v_pk_fma_f32 v[20:21], v[20:21], v[0:1], v[24:25] op_sel_hi:[1,0,1] neg_lo:[0,0,1] neg_hi:[0,0,1]
	global_load_dwordx4 v[24:27], v48, s[14:15]
	global_load_dwordx4 v[194:197], v48, s[14:15] offset:64
	global_load_dwordx4 v[198:201], v48, s[14:15] offset:128
	global_load_dwordx4 v[202:205], v48, s[14:15] offset:192
	global_load_dwordx4 v[206:209], v48, s[14:15] offset:256
	global_load_dwordx4 v[210:213], v48, s[14:15] offset:320
	global_load_dwordx4 v[214:217], v48, s[14:15] offset:384
	global_load_dwordx4 v[218:221], v48, s[14:15] offset:448
	v_pk_mul_f32 v[8:9], v[8:9], v[2:3] op_sel_hi:[1,0]
	v_pk_fma_f32 v[22:23], v[22:23], v[0:1], v[34:35] op_sel_hi:[1,0,1] neg_lo:[0,0,1] neg_hi:[0,0,1]
	v_pk_fma_f32 v[8:9], v[16:17], v[0:1], v[8:9] op_sel_hi:[1,0,1] neg_lo:[0,0,1] neg_hi:[0,0,1]
	v_pk_mul_f32 v[34:35], v[22:23], v[22:23]
	v_pk_mul_f32 v[40:41], v[20:21], v[20:21]
	v_pk_mul_f32 v[10:11], v[10:11], v[2:3] op_sel_hi:[1,0]
	v_mul_f32_e32 v16, v8, v8
	v_pk_mov_b32 v[42:43], v[40:41], v[34:35] op_sel:[1,0]
	v_mov_b32_e32 v41, v35
	v_pk_fma_f32 v[10:11], v[18:19], v[0:1], v[10:11] op_sel_hi:[1,0,1] neg_lo:[0,0,1] neg_hi:[0,0,1]
	v_pk_fma_f32 v[16:17], v[8:9], v[8:9], v[16:17] op_sel_hi:[1,1,0]
	v_pk_add_f32 v[34:35], v[42:43], v[40:41]
	v_mul_f32_e32 v16, v10, v10
	v_pk_mul_f32 v[4:5], v[4:5], v[2:3] op_sel_hi:[1,0]
	v_pk_mul_f32 v[2:3], v[6:7], v[2:3] op_sel_hi:[1,0]
	v_pk_add_f32 v[32:33], v[32:33], v[32:33] op_sel_hi:[0,1]
	v_pk_add_f32 v[34:35], v[34:35], v[34:35] op_sel_hi:[0,1]
	v_pk_fma_f32 v[18:19], v[10:11], v[10:11], v[16:17] op_sel_hi:[1,1,0]
	v_pk_fma_f32 v[6:7], v[14:15], v[0:1], v[2:3] op_sel_hi:[1,0,1] neg_lo:[0,0,1] neg_hi:[0,0,1]
	v_pk_fma_f32 v[12:13], v[12:13], v[0:1], v[4:5] op_sel_hi:[1,0,1] neg_lo:[0,0,1] neg_hi:[0,0,1]
	v_mul_f32_e32 v34, v6, v6
	v_mul_f32_e32 v16, v12, v12
	v_mul_f32_e32 v18, v13, v13
	v_mul_f32_e32 v32, v7, v7
	v_pk_add_f32 v[2:3], v[16:17], v[18:19]
	v_pk_add_f32 v[4:5], v[34:35], v[32:33]
	s_nop 0
	v_pk_add_f32 v[2:3], v[2:3], v[4:5]
	s_nop 0
	v_add_f32_e32 v0, v2, v3
	ds_bpermute_b32 v2, v74, v0
	s_waitcnt lgkmcnt(0)
	v_add_f32_e32 v0, v0, v2
	ds_bpermute_b32 v2, v72, v0
	s_waitcnt lgkmcnt(0)
; __device__ __forceinline__ unsigned pk2(float lo, float hi) { f32x2 v = {lo, hi}; bf16x2_t b = __builtin_convertvector(v, bf16x2_t); return __builtin_bit_cast(unsigned, b); }
; __device__ __forceinline__ void att_final(const AttAcc& A, float l0, float l1, float lam, const float* subg, bf16_t* orow, int g) {
;     ...
;     const float rs = 0.8f / sqrtf(ss * (1.f / 128.f) + EPS);
; #pragma unroll
;     for (int d = 0; d < 8; ++d) { const f32x4 gg = *(const f32x4*)(subg + 16 * d + 4 * g);
;         u32x2 w; w.x = pk2(o[d][0] * rs * gg[0], o[d][1] * rs * gg[1]); w.y = pk2(o[d][2] * rs * gg[2], o[d][3] * rs * gg[3]);
;         *(u32x2*)(orow + 16 * d + 4 * g) = w; }
	v_add_f32_e32 v0, v0, v2
	v_fmamk_f32 v0, v0, 0x3c000000, v166
	v_mul_f32_e32 v2, 0x4f800000, v0
	v_cmp_gt_f32_e32 vcc, s35, v0
	s_nop 1
	v_cndmask_b32_e32 v0, v0, v2, vcc
	v_sqrt_f32_e32 v2, v0
	s_nop 0
	v_add_u32_e32 v3, -1, v2
	v_fma_f32 v4, -v3, v2, v0
	v_cmp_ge_f32_e64 s[2:3], 0, v4
	v_add_u32_e32 v4, 1, v2
	s_nop 0
	v_cndmask_b32_e64 v3, v2, v3, s[2:3]
	v_fma_f32 v2, -v4, v2, v0
	v_cmp_lt_f32_e64 s[2:3], 0, v2
	s_nop 1
	v_cndmask_b32_e64 v2, v3, v4, s[2:3]
	v_mul_f32_e32 v3, 0x37800000, v2
	v_cndmask_b32_e32 v2, v2, v3, vcc
	v_cmp_class_f32_e32 vcc, v0, v167
	s_nop 1
	v_cndmask_b32_e32 v0, v2, v0, vcc
	v_div_scale_f32 v2, s[2:3], v0, v0, s42
	v_rcp_f32_e32 v3, v2
	s_mov_b64 s[2:3], 0
	v_fma_f32 v4, -v2, v3, 1.0
	v_fmac_f32_e32 v3, v4, v3
	v_div_scale_f32 v4, vcc, s42, v0, s42
	v_mul_f32_e32 v5, v4, v3
	v_fma_f32 v14, -v2, v5, v4
	v_fmac_f32_e32 v5, v14, v3
	v_fma_f32 v2, -v2, v5, v4
	v_div_fmas_f32 v2, v2, v3, v5
	v_div_fixup_f32 v14, v2, v0, s42
	v_pk_mul_f32 v[2:3], v[60:61], v[14:15] op_sel_hi:[1,0]
	v_pk_mul_f32 v[4:5], v[62:63], v[14:15] op_sel_hi:[1,0]
	v_lshlrev_b32_e32 v0, 1, v134
	s_waitcnt vmcnt(0)
	v_pk_mul_f32 v[2:3], v[24:25], v[2:3]
	v_pk_mul_f32 v[4:5], v[26:27], v[4:5]
	v_lshl_add_u64 v[16:17], v[150:151], 0, v[0:1]
	v_cvt_pk_bf16_f32 v2, v2, v3
	v_cvt_pk_bf16_f32 v3, v4, v5
	global_store_dwordx2 v[16:17], v[2:3], off
	v_pk_mul_f32 v[18:19], v[52:53], v[14:15] op_sel_hi:[1,0]
	v_pk_mul_f32 v[24:25], v[54:55], v[14:15] op_sel_hi:[1,0]
	v_pk_mul_f32 v[8:9], v[8:9], v[14:15] op_sel_hi:[1,0]
	v_pk_mul_f32 v[10:11], v[10:11], v[14:15] op_sel_hi:[1,0]
	v_pk_mul_f32 v[6:7], v[6:7], v[14:15] op_sel_hi:[1,0]
	v_pk_mul_f32 v[2:3], v[194:195], v[18:19]
	v_pk_mul_f32 v[4:5], v[196:197], v[24:25]
	v_cvt_pk_bf16_f32 v2, v2, v3
	v_cvt_pk_bf16_f32 v3, v4, v5
	global_store_dwordx2 v[16:17], v[2:3], off offset:32
	v_pk_mul_f32 v[18:19], v[44:45], v[14:15] op_sel_hi:[1,0]
	v_pk_mul_f32 v[24:25], v[46:47], v[14:15] op_sel_hi:[1,0]
	v_pk_mul_f32 v[2:3], v[198:199], v[18:19]
	v_pk_mul_f32 v[4:5], v[200:201], v[24:25]
	v_cvt_pk_bf16_f32 v2, v2, v3
	v_cvt_pk_bf16_f32 v3, v4, v5
	global_store_dwordx2 v[16:17], v[2:3], off offset:64
	v_pk_mul_f32 v[18:19], v[36:37], v[14:15] op_sel_hi:[1,0]
	v_pk_mul_f32 v[24:25], v[38:39], v[14:15] op_sel_hi:[1,0]
	v_pk_mul_f32 v[2:3], v[202:203], v[18:19]
	v_pk_mul_f32 v[4:5], v[204:205], v[24:25]
	v_cvt_pk_bf16_f32 v2, v2, v3
	v_cvt_pk_bf16_f32 v3, v4, v5
	global_store_dwordx2 v[16:17], v[2:3], off offset:96
	v_pk_mul_f32 v[18:19], v[28:29], v[14:15] op_sel_hi:[1,0]
	v_pk_mul_f32 v[24:25], v[30:31], v[14:15] op_sel_hi:[1,0]
	v_pk_mul_f32 v[2:3], v[206:207], v[18:19]
	v_pk_mul_f32 v[4:5], v[208:209], v[24:25]
	v_cvt_pk_bf16_f32 v2, v2, v3
	v_cvt_pk_bf16_f32 v3, v4, v5
	global_store_dwordx2 v[16:17], v[2:3], off offset:128
	v_pk_mul_f32 v[18:19], v[20:21], v[14:15] op_sel_hi:[1,0]
	v_pk_mul_f32 v[20:21], v[22:23], v[14:15] op_sel_hi:[1,0]
	v_pk_mul_f32 v[2:3], v[210:211], v[18:19]
	v_pk_mul_f32 v[4:5], v[212:213], v[20:21]
	v_cvt_pk_bf16_f32 v2, v2, v3
	v_cvt_pk_bf16_f32 v3, v4, v5
	global_store_dwordx2 v[16:17], v[2:3], off offset:160
	v_pk_mul_f32 v[2:3], v[214:215], v[8:9]
	v_pk_mul_f32 v[4:5], v[216:217], v[10:11]
	v_cvt_pk_bf16_f32 v2, v2, v3
	v_cvt_pk_bf16_f32 v3, v4, v5
	global_store_dwordx2 v[16:17], v[2:3], off offset:192
	v_pk_mul_f32 v[8:9], v[12:13], v[14:15] op_sel_hi:[1,0]
	v_pk_mul_f32 v[4:5], v[220:221], v[6:7]
	v_pk_mul_f32 v[2:3], v[218:219], v[8:9]
	s_nop 0
	v_cvt_pk_bf16_f32 v2, v2, v3
	v_cvt_pk_bf16_f32 v3, v4, v5
	global_store_dwordx2 v[16:17], v[2:3], off offset:224
